# grid barrier: XCD-leader acquire invalidate issued with the release write-back (both barrier paths now invalidate L1 before waiting)
# baseline (speedup 1.0000x reference)
; __device__ __forceinline__ unsigned xb_add(unsigned* p, unsigned v) { return __hip_atomic_fetch_add(p, v, __ATOMIC_RELAXED, __HIP_MEMORY_SCOPE_AGENT); }
; __device__ __forceinline__ void grid_barrier(unsigned* bar, unsigned x, volatile LAS unsigned* st, unsigned G, int wv) {
;     ...
;         if (old + 1u == (gen + 1u) * nloc) {
;             __builtin_amdgcn_fence(__ATOMIC_RELEASE, "agent");
;             asm volatile("s_waitcnt vmcnt(0)" ::: "memory");
;             const unsigned og = xb_add(&bar[XB_TOP], 1u);
.LBB0_158:
	s_andn2_saveexec_b64 s[8:9], s[8:9]
	s_cbranch_execz .LBB0_178
	s_mov_b64 s[8:9], exec
	buffer_inv sc1
	buffer_wbl2 sc1
	s_waitcnt lgkmcnt(0)
	s_waitcnt vmcnt(0)
	v_mbcnt_lo_u32_b32 v1, s8, 0
	v_mbcnt_hi_u32_b32 v1, s9, v1
	v_cmp_eq_u32_e32 vcc, 0, v1
	s_and_saveexec_b64 s[10:11], vcc
	s_cbranch_execz .LBB0_161
	s_bcnt1_i32_b64 s8, s[8:9]
	v_mov_b32_e32 v2, 0x3000
	v_mov_b32_e32 v3, s8
	global_atomic_add v2, v2, v3, s[78:79] offset:1024 sc0

; __device__ __forceinline__ unsigned xb_ld(unsigned* p)              { return __hip_atomic_load(p, __ATOMIC_RELAXED, __HIP_MEMORY_SCOPE_AGENT); }
; __device__ __forceinline__ unsigned xb_add(unsigned* p, unsigned v) { return __hip_atomic_fetch_add(p, v, __ATOMIC_RELAXED, __HIP_MEMORY_SCOPE_AGENT); }
; #define XB_SPIN(cond, bar) do { unsigned _sp = 0; while (cond) { __builtin_amdgcn_s_sleep(1); \
;     if ((++_sp & 255u) == 0u) { if (xb_ld(&(bar)[XB_TMO])) break; if (_sp > XB_SPIN_CAP) { atomicAdd(&(bar)[XB_TMO], 1u); break; } } } } while (0)
; __device__ __forceinline__ void grid_barrier(unsigned* bar, unsigned x, volatile LAS unsigned* st, unsigned G, int wv) {
;     ...
;             else XB_SPIN(xb_ld(&bar[XB_TOPGEN]) == tg, bar);
;             __builtin_amdgcn_fence(__ATOMIC_ACQUIRE, "agent");
;             xb_add(&bar[XB_XGEN(x)], 1u);
.LBB0_175:
	s_or_b64 exec, exec, s[8:9]
	s_mov_b64 s[8:9], exec
	v_mbcnt_lo_u32_b32 v0, s8, 0
	v_mbcnt_hi_u32_b32 v0, s9, v0
	v_cmp_eq_u32_e32 vcc, 0, v0
	s_waitcnt vmcnt(0)
	s_and_saveexec_b64 s[10:11], vcc
	s_cbranch_execz .LBB0_177
	s_bcnt1_i32_b64 s8, s[8:9]
	v_mov_b32_e32 v0, 0x2000
	v_mov_b32_e32 v1, s8
	global_atomic_add v0, v1, s[6:7] offset:1024

; __device__ __forceinline__ unsigned xb_add(unsigned* p, unsigned v) { return __hip_atomic_fetch_add(p, v, __ATOMIC_RELAXED, __HIP_MEMORY_SCOPE_AGENT); }
; __device__ __forceinline__ void grid_barrier(unsigned* bar, unsigned x, volatile LAS unsigned* st, unsigned G, int wv) {
;     ...
;         if (old + 1u == (gen + 1u) * nloc) {
;             __builtin_amdgcn_fence(__ATOMIC_RELEASE, "agent");
;             asm volatile("s_waitcnt vmcnt(0)" ::: "memory");
;             const unsigned og = xb_add(&bar[XB_TOP], 1u);
.LBB0_438:
	s_andn2_saveexec_b64 s[6:7], s[6:7]
	s_cbranch_execz .LBB0_458
	s_mov_b64 s[6:7], exec
	buffer_inv sc1
	buffer_wbl2 sc1
	s_waitcnt lgkmcnt(0)
	s_waitcnt vmcnt(0)
	v_mbcnt_lo_u32_b32 v1, s6, 0
	v_mbcnt_hi_u32_b32 v1, s7, v1
	v_cmp_eq_u32_e32 vcc, 0, v1
	s_and_saveexec_b64 s[8:9], vcc
	s_cbranch_execz .LBB0_441
	s_bcnt1_i32_b64 s6, s[6:7]
	v_mov_b32_e32 v2, 0x3000
	v_mov_b32_e32 v3, s6
	global_atomic_add v2, v2, v3, s[78:79] offset:1024 sc0

; __device__ __forceinline__ unsigned xb_ld(unsigned* p)              { return __hip_atomic_load(p, __ATOMIC_RELAXED, __HIP_MEMORY_SCOPE_AGENT); }
; __device__ __forceinline__ unsigned xb_add(unsigned* p, unsigned v) { return __hip_atomic_fetch_add(p, v, __ATOMIC_RELAXED, __HIP_MEMORY_SCOPE_AGENT); }
; #define XB_SPIN(cond, bar) do { unsigned _sp = 0; while (cond) { __builtin_amdgcn_s_sleep(1); \
;     if ((++_sp & 255u) == 0u) { if (xb_ld(&(bar)[XB_TMO])) break; if (_sp > XB_SPIN_CAP) { atomicAdd(&(bar)[XB_TMO], 1u); break; } } } } while (0)
; __device__ __forceinline__ void grid_barrier(unsigned* bar, unsigned x, volatile LAS unsigned* st, unsigned G, int wv) {
;     ...
;             else XB_SPIN(xb_ld(&bar[XB_TOPGEN]) == tg, bar);
;             __builtin_amdgcn_fence(__ATOMIC_ACQUIRE, "agent");
;             xb_add(&bar[XB_XGEN(x)], 1u);
.LBB0_455:
	s_or_b64 exec, exec, s[6:7]
	s_mov_b64 s[6:7], exec
	v_mbcnt_lo_u32_b32 v0, s6, 0
	v_mbcnt_hi_u32_b32 v0, s7, v0
	v_cmp_eq_u32_e32 vcc, 0, v0
	s_waitcnt vmcnt(0)
	s_and_saveexec_b64 s[8:9], vcc
	s_cbranch_execz .LBB0_457
	s_bcnt1_i32_b64 s6, s[6:7]
	v_mov_b32_e32 v0, 0x2000
	v_mov_b32_e32 v1, s6
	global_atomic_add v0, v1, s[4:5] offset:1024
